# phase-15 all-fast-path + SBA QK hoist/unmasked section, padded (unexecuted s_nop after unconditional branches) so every later loop keeps the previous version's code placement mod 64
# speedup vs baseline: 1.0172x; 1.0172x over previous
; __device__ __forceinline__ void phase_sba_attn(const Params& p, u16* sm) {
;     ...
;       bf16x8 Lh[2], Ll[2];
; #pragma unroll
;       for (int k2 = 0; k2 < 2; ++k2) {
;         uint32_t hw[4], lw[4];
; #pragma unroll
;         for (int e2 = 0; e2 < 4; ++e2) {
;           const int mt = 2 * k2 + (e2 >> 1), j = (e2 & 1) * 2;
;           hw[e2] = pack2(L[mt][j], L[mt][j + 1]);
;           const float r0 = L[mt][j] - __uint_as_float(hw[e2] << 16), r1 = L[mt][j + 1] - __uint_as_float(hw[e2] & 0xffff0000u);
;           lw[e2] = pack2(r0, r1);
;         }
;         Lh[k2] = mk_frag(hw[0], hw[1], hw[2], hw[3]);
;         Ll[k2] = mk_frag(lw[0], lw[1], lw[2], lw[3]);
;       }
;       f32x4 cum[4];
; #pragma unroll
;       for (int ms = 0; ms < 4; ++ms) {
;         const int a = ms >> 1, bb = ms & 1;
;         f32x4 c = (f32x4){0.f, 0.f, 0.f, 0.f};
;         c = mfma16(tri[bb], Lh[a], c);
;         c = mfma16(tri[bb], Ll[a], c);
;         if (a == 0) { c = mfma16(ones, Lh[1], c); c = mfma16(ones, Ll[1], c); }
;         cum[ms] = c;
;       }
;       float tot = cum[0][0] + L[0][0];
;       tot = __shfl(tot, fr);
;       bf16x8 pf[2];
; #pragma unroll
;       for (int k2 = 0; k2 < 2; ++k2) {
;         uint32_t pw[4];
; #pragma unroll
;         for (int e2 = 0; e2 < 4; ++e2) {
;           const int mt = 2 * k2 + (e2 >> 1), j = (e2 & 1) * 2;
;           float p0 = __builtin_amdgcn_exp2f(lb[mt][j] + cum[mt][j] + carry);
;           float p1 = __builtin_amdgcn_exp2f(lb[mt][j + 1] + cum[mt][j + 1] + carry);
.LBB0_335:
	s_or_b64 exec, exec, s[8:9]
	s_nop 1
	v_cvt_pk_bf16_f32 v44, v2, v3
	v_lshlrev_b32_e32 v46, 16, v44
	v_and_b32_e32 v47, 0xffff0000, v44
	v_pk_add_f32 v[46:47], v[2:3], v[46:47] neg_lo:[0,1] neg_hi:[0,1]
	v_cvt_pk_bf16_f32 v45, v116, v117
	v_cvt_pk_bf16_f32 v48, v46, v47
	v_lshlrev_b32_e32 v3, 16, v45
	v_and_b32_e32 v46, 0xffff0000, v45
	v_sub_f32_e32 v3, v116, v3
	v_sub_f32_e32 v46, v117, v46
	v_cvt_pk_bf16_f32 v49, v3, v46
	v_cvt_pk_bf16_f32 v46, v118, v119
	v_lshlrev_b32_e32 v3, 16, v46
	v_and_b32_e32 v47, 0xffff0000, v46
	v_sub_f32_e32 v3, v118, v3
	v_sub_f32_e32 v47, v119, v47
	v_cvt_pk_bf16_f32 v50, v3, v47
	v_cvt_pk_bf16_f32 v47, v120, v121
	v_lshlrev_b32_e32 v3, 16, v47
	v_and_b32_e32 v51, 0xffff0000, v47
	v_sub_f32_e32 v3, v120, v3
	v_sub_f32_e32 v51, v121, v51
	v_cvt_pk_bf16_f32 v52, v123, v124
	v_cvt_pk_bf16_f32 v51, v3, v51
	v_lshlrev_b32_e32 v3, 16, v52
	v_and_b32_e32 v53, 0xffff0000, v52
	v_sub_f32_e32 v3, v123, v3
	v_sub_f32_e32 v53, v124, v53
	v_cvt_pk_bf16_f32 v56, v3, v53
	v_cvt_pk_bf16_f32 v53, v125, v126
	v_lshlrev_b32_e32 v3, 16, v53
	v_and_b32_e32 v54, 0xffff0000, v53
	v_sub_f32_e32 v3, v125, v3
	v_sub_f32_e32 v54, v126, v54
	v_cvt_pk_bf16_f32 v57, v3, v54
	v_cvt_pk_bf16_f32 v54, v127, v128
	v_mfma_f32_16x16x32_bf16 v[116:119], v[8:11], v[44:47], 0
	v_lshlrev_b32_e32 v3, 16, v54
	s_mov_b32 s18, s16
	s_mov_b32 s19, s16
	v_sub_f32_e32 v3, v127, v3
	s_mov_b32 s17, s16
	v_mov_b64_e32 v[126:127], s[18:19]
	v_mov_b64_e32 v[124:125], s[16:17]
	v_mfma_f32_16x16x32_bf16 v[116:119], v[8:11], v[48:51], v[116:119]
	v_and_b32_e32 v55, 0xffff0000, v54
	v_sub_f32_e32 v55, v128, v55
	v_cvt_pk_bf16_f32 v58, v3, v55
	v_mfma_f32_16x16x32_bf16 v[44:47], v[4:7], v[44:47], 0
	v_cvt_pk_bf16_f32 v55, v130, v129
	v_lshlrev_b32_e32 v3, 16, v55
	v_and_b32_e32 v59, 0xffff0000, v55
	v_mfma_f32_16x16x32_bf16 v[116:119], v[124:127], v[52:55], v[116:119]
	v_sub_f32_e32 v3, v130, v3
	v_sub_f32_e32 v59, v129, v59
	v_cvt_pk_bf16_f32 v59, v3, v59
	v_mfma_f32_16x16x32_bf16 v[44:47], v[4:7], v[48:51], v[44:47]
	s_nop 0
	v_mfma_f32_16x16x32_bf16 v[116:119], v[124:127], v[56:59], v[116:119]
	v_mfma_f32_16x16x32_bf16 v[44:47], v[124:127], v[52:55], v[44:47]
	v_mfma_f32_16x16x32_bf16 v[48:51], v[8:11], v[52:55], 0
	s_nop 5
	v_add_f32_e32 v3, v78, v116
	v_add_f32_e32 v3, v0, v3
	v_exp_f32_e32 v3, v3
	v_mfma_f32_16x16x32_bf16 v[52:55], v[4:7], v[52:55], 0
	v_add_f32_e32 v2, v2, v116
	ds_bpermute_b32 v2, v112, v2
	v_mfma_f32_16x16x32_bf16 v[44:47], v[124:127], v[56:59], v[44:47]
	v_mfma_f32_16x16x32_bf16 v[48:51], v[8:11], v[56:59], v[48:51]
	v_mfma_f32_16x16x32_bf16 v[52:55], v[4:7], v[56:59], v[52:55]
	v_add_f32_e32 v56, v79, v117
	v_add_f32_e32 v56, v0, v56
	v_exp_f32_e32 v56, v56
	s_andn2_b64 s[8:9], exec, vcc
	s_cbranch_scc0 .Lsba_um
; __device__ __forceinline__ void phase_sba_attn(const Params& p, u16* sm) {
;     ...
;       bf16x8 pf[2];
; #pragma unroll
;       for (int k2 = 0; k2 < 2; ++k2) {
;         uint32_t pw[4];
; #pragma unroll
;         for (int e2 = 0; e2 < 4; ++e2) {
;           const int mt = 2 * k2 + (e2 >> 1), j = (e2 & 1) * 2;
;           float p0 = __builtin_amdgcn_exp2f(lb[mt][j] + cum[mt][j] + carry);
;           float p1 = __builtin_amdgcn_exp2f(lb[mt][j + 1] + cum[mt][j + 1] + carry);
;           if (tile_masked) {
;             p0 = ((vmask >> (mt * 4 + j)) & 1u) ? p0 : 0.f;
;             p1 = ((vmask >> (mt * 4 + j + 1)) & 1u) ? p1 : 0.f;
;           }
;           pw[e2] = pack2(p0, p1);
;         }
;         pf[k2] = mk_frag(pw[0], pw[1], pw[2], pw[3]);
;       }
; #pragma unroll
;       for (int k2 = 0; k2 < 2; ++k2)
; #pragma unroll
;         for (int dm = 0; dm < 4; ++dm) {
;           bf16x8 vf = *(const bf16x8*)(sV + (dm * 16 + fr) * LDSP + k2 * 32 + fq * 8);
;           o[dm] = mfma16(vf, pf[k2], o[dm]);
;         }
;       carry += tot;
	v_and_b32_e32 v57, 1, v122
	v_cmp_eq_u32_e64 s[8:9], 1, v57
	v_and_b32_e32 v57, 2, v122
	v_cmp_ne_u32_e64 s[10:11], 0, v57
	s_or_b64 s[8:9], vcc, s[8:9]
	v_cndmask_b32_e64 v3, 0, v3, s[8:9]
	s_or_b64 s[8:9], vcc, s[10:11]
	v_cndmask_b32_e64 v56, 0, v56, s[8:9]
	v_cvt_pk_bf16_f32 v56, v3, v56
	v_add_f32_e32 v3, v80, v118
	v_add_f32_e32 v3, v0, v3
	v_add_f32_e32 v57, v81, v119
	v_exp_f32_e32 v3, v3
	v_add_f32_e32 v57, v0, v57
	v_exp_f32_e32 v57, v57
	v_and_b32_e32 v58, 4, v122
	v_cmp_ne_u32_e64 s[8:9], 0, v58
	v_and_b32_e32 v58, 8, v122
	v_cmp_ne_u32_e64 s[10:11], 0, v58
	s_or_b64 s[8:9], vcc, s[8:9]
	v_cndmask_b32_e64 v3, 0, v3, s[8:9]
	s_or_b64 s[8:9], vcc, s[10:11]
	v_cndmask_b32_e64 v57, 0, v57, s[8:9]
	v_cvt_pk_bf16_f32 v57, v3, v57
	v_add_f32_e32 v3, v82, v44
	v_add_f32_e32 v3, v0, v3
	v_add_f32_e32 v44, v83, v45
	v_exp_f32_e32 v3, v3
	v_add_f32_e32 v44, v0, v44
	v_exp_f32_e32 v44, v44
	v_and_b32_e32 v45, 16, v122
	v_cmp_ne_u32_e64 s[8:9], 0, v45
	v_and_b32_e32 v45, 32, v122
	v_cmp_ne_u32_e64 s[10:11], 0, v45
	s_or_b64 s[8:9], vcc, s[8:9]
	v_cndmask_b32_e64 v3, 0, v3, s[8:9]
	s_or_b64 s[8:9], vcc, s[10:11]
	v_cndmask_b32_e64 v44, 0, v44, s[8:9]
	v_cvt_pk_bf16_f32 v58, v3, v44
	v_add_f32_e32 v3, v84, v46
	v_add_f32_e32 v3, v0, v3
	v_add_f32_e32 v44, v85, v47
	v_exp_f32_e32 v3, v3
	v_add_f32_e32 v44, v0, v44
	v_exp_f32_e32 v44, v44
	v_and_b32_e32 v45, 64, v122
	v_cmp_ne_u32_e64 s[8:9], 0, v45
	v_and_b32_e32 v45, 0x80, v122
	v_cmp_ne_u32_e64 s[10:11], 0, v45
	s_or_b64 s[8:9], vcc, s[8:9]
	v_cndmask_b32_e64 v3, 0, v3, s[8:9]
	s_or_b64 s[8:9], vcc, s[10:11]
	v_cndmask_b32_e64 v44, 0, v44, s[8:9]
	v_cvt_pk_bf16_f32 v59, v3, v44
	v_add_f32_e32 v3, v86, v48
	v_add_f32_e32 v3, v0, v3
	v_add_f32_e32 v44, v87, v49
	v_exp_f32_e32 v3, v3
	v_add_f32_e32 v44, v0, v44
	v_exp_f32_e32 v44, v44
	v_and_b32_e32 v45, 0x100, v122
	v_cmp_ne_u32_e64 s[8:9], 0, v45
	v_and_b32_e32 v45, 0x200, v122
	v_cmp_ne_u32_e64 s[10:11], 0, v45
	s_or_b64 s[8:9], vcc, s[8:9]
	v_cndmask_b32_e64 v3, 0, v3, s[8:9]
	s_or_b64 s[8:9], vcc, s[10:11]
	v_cndmask_b32_e64 v44, 0, v44, s[8:9]
	v_cvt_pk_bf16_f32 v44, v3, v44
	v_add_f32_e32 v3, v88, v50
	v_add_f32_e32 v3, v0, v3
	v_add_f32_e32 v45, v89, v51
	v_exp_f32_e32 v3, v3
	v_add_f32_e32 v45, v0, v45
	v_exp_f32_e32 v45, v45
	v_and_b32_e32 v46, 0x400, v122
	v_cmp_ne_u32_e64 s[8:9], 0, v46
	v_and_b32_e32 v46, 0x800, v122
	v_cmp_ne_u32_e64 s[10:11], 0, v46
	s_or_b64 s[8:9], vcc, s[8:9]
	v_cndmask_b32_e64 v3, 0, v3, s[8:9]
	s_or_b64 s[8:9], vcc, s[10:11]
	v_cndmask_b32_e64 v45, 0, v45, s[8:9]
	v_cvt_pk_bf16_f32 v45, v3, v45
	v_add_f32_e32 v3, v90, v52
	v_add_f32_e32 v3, v0, v3
	v_add_f32_e32 v46, v91, v53
	v_exp_f32_e32 v3, v3
	v_add_f32_e32 v46, v0, v46
	v_exp_f32_e32 v46, v46
	v_and_b32_e32 v47, 0x1000, v122
	v_cmp_ne_u32_e64 s[8:9], 0, v47
	v_and_b32_e32 v47, 0x2000, v122
	v_cmp_ne_u32_e64 s[10:11], 0, v47
	s_or_b64 s[8:9], vcc, s[8:9]
	v_cndmask_b32_e64 v3, 0, v3, s[8:9]
	s_or_b64 s[8:9], vcc, s[10:11]
	v_cndmask_b32_e64 v46, 0, v46, s[8:9]
	v_cvt_pk_bf16_f32 v46, v3, v46
	v_add_f32_e32 v3, v92, v54
	ds_read_b128 v[48:51], v115 offset:9216
	v_add_f32_e32 v47, v93, v55
	ds_read_b128 v[52:55], v115 offset:11520
	ds_read_b128 v[78:81], v115 offset:13824
	ds_read_b128 v[82:85], v115 offset:9280
	v_and_b32_e32 v86, 0x4000, v122
	s_waitcnt lgkmcnt(2)
	v_mfma_f32_16x16x32_bf16 v[36:39], v[52:55], v[56:59], v[36:39]
	v_and_b32_e32 v52, 0x8000, v122
	v_cmp_ne_u32_e64 s[8:9], 0, v86
	v_cmp_ne_u32_e64 s[10:11], 0, v52
	v_mfma_f32_16x16x32_bf16 v[40:43], v[48:51], v[56:59], v[40:43]
	ds_read_b128 v[48:51], v115 offset:16128
	ds_read_b128 v[86:89], v115 offset:11584
	ds_read_b128 v[52:55], v115 offset:13888
	v_add_f32_e32 v3, v0, v3
	s_waitcnt lgkmcnt(4)
	v_mfma_f32_16x16x32_bf16 v[24:27], v[78:81], v[56:59], v[24:27]
	ds_read_b128 v[78:81], v115 offset:16192
	v_add_f32_e32 v47, v0, v47
	v_exp_f32_e32 v3, v3
	v_exp_f32_e32 v47, v47
	s_waitcnt lgkmcnt(3)
	v_mfma_f32_16x16x32_bf16 v[20:23], v[48:51], v[56:59], v[20:23]
	s_or_b64 s[8:9], vcc, s[8:9]
	s_or_b64 vcc, vcc, s[10:11]
	v_cndmask_b32_e64 v3, 0, v3, s[8:9]
	v_cndmask_b32_e32 v47, 0, v47, vcc
	v_cvt_pk_bf16_f32 v47, v3, v47
	v_add_f32_e32 v0, v0, v2
	s_nop 0
	v_mfma_f32_16x16x32_bf16 v[40:43], v[82:85], v[44:47], v[40:43]
	s_waitcnt lgkmcnt(2)
	v_mfma_f32_16x16x32_bf16 v[36:39], v[86:89], v[44:47], v[36:39]
	s_waitcnt lgkmcnt(1)
	v_mfma_f32_16x16x32_bf16 v[24:27], v[52:55], v[44:47], v[24:27]
	s_waitcnt lgkmcnt(0)
	v_mfma_f32_16x16x32_bf16 v[20:23], v[78:81], v[44:47], v[20:23]
	s_branch .LBB0_336
	s_nop 0
	s_nop 0
	s_nop 0
	s_nop 0
	s_nop 0
	s_nop 0
	s_nop 0
	s_nop 0
	s_nop 0
	s_nop 0

; __device__ __forceinline__ void phase_nsa_sw(const Params& p, u16* sm) {
;     ...
;     for (int i = 0; i < ntl; ++i) {
;       __syncthreads();
;       const int v = lst[i];
;       const u16* cK = sK + (i & 1) * 2 * 64 * LDSP;
;       const u16* cV = sV + (i & 1) * 2 * 64 * LDSP;
;       if (i == nsel) {
.Lfp15_tail:
	s_add_i32 s10, s42, 1
	v_cmp_ge_i32_e64 s[8:9], s10, v231
	s_add_i32 s83, s83, 4
	s_addk_i32 s89, 0x80
	s_and_b64 vcc, exec, s[8:9]
	s_cbranch_vccnz .LBB0_1323
	s_mov_b32 s42, s10
	v_readfirstlane_b32 s11, v192
	s_nop 3
	s_cmp_lt_u32 s11, 0x100
	s_cbranch_scc1 .LBB0_1336
	v_readlane_b32 s14, v24, s42
	v_readlane_b32 s15, v25, s42
	v_cmp_ne_u32_e32 vcc, s42, v203
	s_cmp_lt_u32 s42, 64
	s_cselect_b32 s14, s14, s15
	s_cbranch_vccz .Lfp15_park
	s_branch .Lfp15_dispatch
	s_nop 0
	s_nop 0
	s_nop 0
	s_nop 0
	s_nop 0
	s_nop 0
	s_nop 0
	s_nop 0
	s_nop 0
	s_nop 0
	s_nop 0
	s_nop 0
	s_nop 0
	s_nop 0
	s_nop 0

; template <bool MASKED>
; __device__ __forceinline__ void nsa_online_step(NsaState& st, f32x4 (&s)[2][4], unsigned vmask, bool lanevalid, const u16* sV, int fr, int fq) {
;     ...
;     tmax = fmaxf(tmax, __shfl_xor(tmax, 16));
;     tmax = fmaxf(tmax, __shfl_xor(tmax, 32));
;     const bool upd = tmax > st.m[hh] + DEFER;
;     if (__ballot(upd) != 0ull) {
;       const float mnew = upd ? tmax : st.m[hh];
;       const float alpha = __builtin_amdgcn_exp2f((st.m[hh] - mnew) * SM_C);
;       st.m[hh] = mnew;
; #pragma unroll
;       for (int dm = 0; dm < 4; ++dm) st.acc[hh][dm] *= alpha;
;       st.accL[hh] *= alpha;
;     }
.Lfp15m_upd1:
	v_cndmask_b32_e64 v1, v221, v1, s[30:31]
	v_mov_b32_e32 v3, v1
	s_nop 1
	v_permlane16_swap_b32_e32 v1, v3
	s_nop 0
	v_max_f32_e32 v1, v1, v3
	v_mov_b32_e32 v3, v1
	s_nop 1
	v_permlane32_swap_b32_e32 v1, v3
	s_nop 0
	v_max_f32_e32 v1, v1, v3
	v_cmp_gt_f32_e32 vcc, v1, v168
	s_nop 1
	v_cndmask_b32_e32 v3, v235, v1, vcc
	v_sub_f32_e32 v1, v235, v3
	v_mul_f32_e32 v168, 0x3e38aa3b, v1
	v_exp_f32_e32 v168, v168
	v_mov_b32_e32 v235, v3
	s_nop 0
	v_pk_mul_f32 v[132:133], v[132:133], v[168:169] op_sel_hi:[1,0]
	v_pk_mul_f32 v[134:135], v[134:135], v[168:169] op_sel_hi:[1,0]
	v_pk_mul_f32 v[116:117], v[116:117], v[168:169] op_sel_hi:[1,0]
	v_pk_mul_f32 v[118:119], v[118:119], v[168:169] op_sel_hi:[1,0]
	v_pk_mul_f32 v[112:113], v[112:113], v[168:169] op_sel_hi:[1,0]
	v_pk_mul_f32 v[114:115], v[114:115], v[168:169] op_sel_hi:[1,0]
	v_pk_mul_f32 v[108:109], v[108:109], v[168:169] op_sel_hi:[1,0]
	v_pk_mul_f32 v[110:111], v[110:111], v[168:169] op_sel_hi:[1,0]
	v_pk_mul_f32 v[104:105], v[104:105], v[168:169] op_sel_hi:[1,0]
	v_pk_mul_f32 v[106:107], v[106:107], v[168:169] op_sel_hi:[1,0]
	s_branch .Lfp15m_noupd1
	s_nop 0
	s_nop 0
